# P2 sk_tile: coalesced row-contiguous loads, LDS transpose to MFMA layout, 5-step prefetch
# speedup vs baseline: 1.0137x; 1.0137x over previous
; #define LAS __attribute__((address_space(3)))
; __device__ __forceinline__ unsigned long long rt() { return __builtin_amdgcn_s_memrealtime(); }
; __device__ __forceinline__ unsigned cvtpk(float lo, float hi) { f32x2_t v = {lo, hi}; bf16x2_t b = __builtin_convertvector(v, bf16x2_t); return __builtin_bit_cast(unsigned, b); }
; #define MFMA16(a, b, c) __builtin_amdgcn_mfma_f32_16x16x32_bf16((a), (b), (c), 0, 0, 0)
; __device__ __forceinline__ void sk_tile(LAS unsigned char* lds, const bf16* A, int lda, const bf16* Wt, int K, int r0, int c0, int tid, int wave, int lane) {
;     const int r16 = lane & 15, kg = lane >> 4;
;     const int ksl = K >> 3, k0 = wave * ksl;
;     const bf16* ap = A + (size_t)(r0 + r16) * lda + k0 + 8 * kg;
;     const bf16* bp = Wt + (size_t)(c0 + r16) * K + k0 + 8 * kg;
;     f32x4 acc[2][4];
; #pragma unroll
;     for (int m = 0; m < 2; ++m)
; #pragma unroll
;         for (int j = 0; j < 4; ++j) acc[m][j] = (f32x4){0.f, 0.f, 0.f, 0.f};
; #pragma unroll 2
;     for (int ks = 0; ks < (ksl >> 5); ++ks) {
;         bf16x8 af[2], bf[4];
; #pragma unroll
;         for (int m = 0; m < 2; ++m) af[m] = *(const bf16x8*)(ap + (size_t)(16 * m) * lda + 32 * ks);
; #pragma unroll
;         for (int j = 0; j < 4; ++j) bf[j] = *(const bf16x8*)(bp + (size_t)(16 * j) * K + 32 * ks);
; #pragma unroll
;         for (int m = 0; m < 2; ++m)
; #pragma unroll
;             for (int j = 0; j < 4; ++j) acc[m][j] = MFMA16(af[m], bf[j], acc[m][j]);
;     }
; __device__ __forceinline__ void sk_gemm_y(LAS unsigned char* lds, const bf16* A, int lda, const bf16* Wt, int K, bf16* Y, int tid, int wave, int lane) {
;     for (int item = blockIdx.x; item < 256; item += gridDim.x) {
;         const int rt = item >> 4, ct = item & 15;
;         sk_tile(lds, A, lda, Wt, K, MP + 32 * rt, 64 * ct, tid, wave, lane);
;         const f32x4 v = ((const LAS f32x4*)(lds + 65536))[tid];
;         *(uint2*)(Y + (size_t)(MP + 32 * rt + (tid >> 4)) * D + 64 * ct + 4 * (tid & 15)) = make_uint2(cvtpk(v[0], v[1]), cvtpk(v[2], v[3]));
.LBB0_429:
	s_and_b32 s16, s4, 0xffffffe0
	s_and_b32 s0, s2, 0x3c0
	s_addk_i32 s16, 0x4000
	v_lshrrev_b32_e32 v59, 4, v162
	v_and_b32_e32 v58, 3, v162
	v_sub_u32_e32 v59, 0, v59
	v_xor_b32_e32 v58, v58, v59
	v_and_b32_e32 v58, 3, v58
	v_lshlrev_b32_e32 v58, 4, v58
	v_and_b32_e32 v59, 48, v162
	v_sub_u32_e32 v58, v58, v59
	v_ashrrev_i32_e32 v59, 31, v58
	v_lshrrev_b32_e32 v70, 2, v162
	v_readlane_b32 s98, v254, 34
	s_nop 3
	s_lshl_b32 s98, s98, 14
	v_lshl_add_u32 v68, v162, 4, s98
	v_and_b32_e32 v69, 15, v162
	v_lshrrev_b32_e32 v71, 2, v69
	v_sub_u32_e32 v71, 0, v71
	v_lshlrev_b32_e32 v69, 6, v69
	v_lshrrev_b32_e32 v2, 4, v162
	v_xor_b32_e32 v71, v71, v2
	v_and_b32_e32 v71, 3, v71
	v_lshl_add_u32 v69, v71, 4, v69
	v_add_u32_e32 v69, s98, v69
	v_or_b32_e32 v2, s0, v70
	v_or_b32_e32 v3, s16, v70
	v_mul_u32_u24_e32 v2, 0xb00, v2
	v_mad_i64_i32 v[44:45], s[18:19], v3, s6, v[8:9]
	v_lshlrev_b32_e32 v6, 1, v2
	s_mov_b64 s[98:99], 0x16000
	s_mov_b64 s[100:101], 0x2c000
	v_lshl_add_u64 v[60:61], v[10:11], 0, v[6:7]
	v_lshl_add_u64 v[44:45], v[44:45], 0, v[58:59]
	v_lshl_add_u64 v[60:61], v[60:61], 0, v[58:59]
	v_lshl_add_u64 v[46:47], v[44:45], 0, s[98:99]
	v_lshl_add_u64 v[62:63], v[60:61], 0, s[98:99]
	v_lshl_add_u64 v[64:65], v[60:61], 0, s[100:101]
	s_mov_b64 s[100:101], 0x42000
	v_lshl_add_u64 v[66:67], v[60:61], 0, s[100:101]
	s_lshl_b32 s0, s0, 1
	v_or_b32_e32 v58, s16, v25
	v_ashrrev_i32_e32 v59, 31, v58
	v_lshlrev_b64 v[56:57], 11, v[58:59]
	v_lshl_add_u64 v[58:59], s[20:21], 0, v[56:57]
	v_lshl_add_u64 v[58:59], v[58:59], 0, s[0:1]
	v_lshl_add_u64 v[56:57], v[58:59], 0, v[12:13]
	s_add_i32 s7, s7, s87
	s_add_i32 s2, s2, s3
	s_add_i32 s4, s4, s5
	s_cmpk_lt_i32 s7, 0x100
	global_load_dwordx4 v[120:123], v[44:45], off
	global_load_dwordx4 v[124:127], v[46:47], off
	global_load_dwordx4 v[128:131], v[60:61], off
	global_load_dwordx4 v[132:135], v[62:63], off
	global_load_dwordx4 v[136:139], v[64:65], off
	global_load_dwordx4 v[140:143], v[66:67], off
	global_load_dwordx4 v[144:147], v[44:45], off offset:64
	global_load_dwordx4 v[148:151], v[46:47], off offset:64
	global_load_dwordx4 v[152:155], v[60:61], off offset:64
	global_load_dwordx4 v[156:159], v[62:63], off offset:64
	global_load_dwordx4 v[168:171], v[64:65], off offset:64
	global_load_dwordx4 v[172:175], v[66:67], off offset:64
	global_load_dwordx4 v[176:179], v[44:45], off offset:128
	global_load_dwordx4 v[180:183], v[46:47], off offset:128
	global_load_dwordx4 v[184:187], v[60:61], off offset:128
	global_load_dwordx4 v[188:191], v[62:63], off offset:128
	global_load_dwordx4 v[192:195], v[64:65], off offset:128
	global_load_dwordx4 v[196:199], v[66:67], off offset:128
	global_load_dwordx4 v[200:203], v[44:45], off offset:192
	global_load_dwordx4 v[204:207], v[46:47], off offset:192
	global_load_dwordx4 v[208:211], v[60:61], off offset:192
	global_load_dwordx4 v[212:215], v[62:63], off offset:192
	global_load_dwordx4 v[216:219], v[64:65], off offset:192
	global_load_dwordx4 v[220:223], v[66:67], off offset:192
	global_load_dwordx4 v[224:227], v[44:45], off offset:256
	global_load_dwordx4 v[228:231], v[46:47], off offset:256
	global_load_dwordx4 v[232:235], v[60:61], off offset:256
	global_load_dwordx4 v[236:239], v[62:63], off offset:256
	global_load_dwordx4 v[240:243], v[64:65], off offset:256
	global_load_dwordx4 v[244:247], v[66:67], off offset:256
	s_waitcnt vmcnt(24)
	ds_write_b128 v68, v[120:123] offset:0
	ds_write_b128 v68, v[124:127] offset:1024
	ds_write_b128 v68, v[128:131] offset:2048
	ds_write_b128 v68, v[132:135] offset:3072
	ds_write_b128 v68, v[136:139] offset:4096
	ds_write_b128 v68, v[140:143] offset:5120
	ds_read_b128 v[72:75], v69 offset:0
	ds_read_b128 v[76:79], v69 offset:1024
	ds_read_b128 v[80:83], v69 offset:2048
	ds_read_b128 v[84:87], v69 offset:3072
	ds_read_b128 v[88:91], v69 offset:4096
	ds_read_b128 v[92:95], v69 offset:5120
	s_waitcnt vmcnt(18)
	ds_write_b128 v68, v[144:147] offset:6144
	ds_write_b128 v68, v[148:151] offset:7168
	ds_write_b128 v68, v[152:155] offset:8192
	ds_write_b128 v68, v[156:159] offset:9216
	ds_write_b128 v68, v[168:171] offset:10240
	ds_write_b128 v68, v[172:175] offset:11264
	ds_read_b128 v[96:99], v69 offset:6144
	ds_read_b128 v[100:103], v69 offset:7168
	ds_read_b128 v[104:107], v69 offset:8192
	ds_read_b128 v[108:111], v69 offset:9216
	ds_read_b128 v[112:115], v69 offset:10240
	ds_read_b128 v[116:119], v69 offset:11264
	s_waitcnt lgkmcnt(12)
	global_load_dwordx4 v[120:123], v[44:45], off offset:320
	global_load_dwordx4 v[124:127], v[46:47], off offset:320
	global_load_dwordx4 v[128:131], v[60:61], off offset:320
	global_load_dwordx4 v[132:135], v[62:63], off offset:320
	global_load_dwordx4 v[136:139], v[64:65], off offset:320
	global_load_dwordx4 v[140:143], v[66:67], off offset:320
	v_mfma_f32_16x16x32_bf16 v[18:21], v[72:75], v[80:83], 0
	v_mfma_f32_16x16x32_bf16 v[48:51], v[72:75], v[84:87], 0
	v_mfma_f32_16x16x32_bf16 v[52:55], v[72:75], v[88:91], 0
	v_mfma_f32_16x16x32_bf16 v[28:31], v[72:75], v[92:95], 0
	v_mfma_f32_16x16x32_bf16 v[32:35], v[76:79], v[80:83], 0
	v_mfma_f32_16x16x32_bf16 v[36:39], v[76:79], v[84:87], 0
	v_mfma_f32_16x16x32_bf16 v[40:43], v[76:79], v[88:91], 0
	v_mfma_f32_16x16x32_bf16 v[2:5], v[76:79], v[92:95], 0
	s_waitcnt vmcnt(18)
	ds_write_b128 v68, v[176:179] offset:0
	ds_write_b128 v68, v[180:183] offset:1024
	ds_write_b128 v68, v[184:187] offset:2048
	ds_write_b128 v68, v[188:191] offset:3072
	ds_write_b128 v68, v[192:195] offset:4096
	ds_write_b128 v68, v[196:199] offset:5120
	ds_read_b128 v[72:75], v69 offset:0
	ds_read_b128 v[76:79], v69 offset:1024
	ds_read_b128 v[80:83], v69 offset:2048
	ds_read_b128 v[84:87], v69 offset:3072
	ds_read_b128 v[88:91], v69 offset:4096
	ds_read_b128 v[92:95], v69 offset:5120
	s_waitcnt lgkmcnt(12)
; #define MFMA16(a, b, c) __builtin_amdgcn_mfma_f32_16x16x32_bf16((a), (b), (c), 0, 0, 0)
; __device__ __forceinline__ void sk_tile(LAS unsigned char* lds, const bf16* A, int lda, const bf16* Wt, int K, int r0, int c0, int tid, int wave, int lane) {
;     ...
; #pragma unroll 2
;     for (int ks = 0; ks < (ksl >> 5); ++ks) {
;         bf16x8 af[2], bf[4];
; #pragma unroll
;         for (int m = 0; m < 2; ++m) af[m] = *(const bf16x8*)(ap + (size_t)(16 * m) * lda + 32 * ks);
; #pragma unroll
;         for (int j = 0; j < 4; ++j) bf[j] = *(const bf16x8*)(bp + (size_t)(16 * j) * K + 32 * ks);
; #pragma unroll
;         for (int m = 0; m < 2; ++m)
; #pragma unroll
;             for (int j = 0; j < 4; ++j) acc[m][j] = MFMA16(af[m], bf[j], acc[m][j]);
;     }
	global_load_dwordx4 v[144:147], v[44:45], off offset:384
	global_load_dwordx4 v[148:151], v[46:47], off offset:384
	global_load_dwordx4 v[152:155], v[60:61], off offset:384
	global_load_dwordx4 v[156:159], v[62:63], off offset:384
	global_load_dwordx4 v[168:171], v[64:65], off offset:384
	global_load_dwordx4 v[172:175], v[66:67], off offset:384
	v_mfma_f32_16x16x32_bf16 v[18:21], v[96:99], v[104:107], v[18:21]
	v_mfma_f32_16x16x32_bf16 v[48:51], v[96:99], v[108:111], v[48:51]
	v_mfma_f32_16x16x32_bf16 v[52:55], v[96:99], v[112:115], v[52:55]
	v_mfma_f32_16x16x32_bf16 v[28:31], v[96:99], v[116:119], v[28:31]
	v_mfma_f32_16x16x32_bf16 v[32:35], v[100:103], v[104:107], v[32:35]
	v_mfma_f32_16x16x32_bf16 v[36:39], v[100:103], v[108:111], v[36:39]
	v_mfma_f32_16x16x32_bf16 v[40:43], v[100:103], v[112:115], v[40:43]
	v_mfma_f32_16x16x32_bf16 v[2:5], v[100:103], v[116:119], v[2:5]
	s_waitcnt vmcnt(18)
	ds_write_b128 v68, v[200:203] offset:6144
	ds_write_b128 v68, v[204:207] offset:7168
	ds_write_b128 v68, v[208:211] offset:8192
	ds_write_b128 v68, v[212:215] offset:9216
	ds_write_b128 v68, v[216:219] offset:10240
	ds_write_b128 v68, v[220:223] offset:11264
	ds_read_b128 v[96:99], v69 offset:6144
	ds_read_b128 v[100:103], v69 offset:7168
	ds_read_b128 v[104:107], v69 offset:8192
	ds_read_b128 v[108:111], v69 offset:9216
	ds_read_b128 v[112:115], v69 offset:10240
	ds_read_b128 v[116:119], v69 offset:11264
	s_waitcnt lgkmcnt(12)
	global_load_dwordx4 v[176:179], v[44:45], off offset:448
	global_load_dwordx4 v[180:183], v[46:47], off offset:448
	global_load_dwordx4 v[184:187], v[60:61], off offset:448
	global_load_dwordx4 v[188:191], v[62:63], off offset:448
	global_load_dwordx4 v[192:195], v[64:65], off offset:448
	global_load_dwordx4 v[196:199], v[66:67], off offset:448
	v_mfma_f32_16x16x32_bf16 v[18:21], v[72:75], v[80:83], v[18:21]
	v_mfma_f32_16x16x32_bf16 v[48:51], v[72:75], v[84:87], v[48:51]
	v_mfma_f32_16x16x32_bf16 v[52:55], v[72:75], v[88:91], v[52:55]
	v_mfma_f32_16x16x32_bf16 v[28:31], v[72:75], v[92:95], v[28:31]
	v_mfma_f32_16x16x32_bf16 v[32:35], v[76:79], v[80:83], v[32:35]
	v_mfma_f32_16x16x32_bf16 v[36:39], v[76:79], v[84:87], v[36:39]
	v_mfma_f32_16x16x32_bf16 v[40:43], v[76:79], v[88:91], v[40:43]
	v_mfma_f32_16x16x32_bf16 v[2:5], v[76:79], v[92:95], v[2:5]
	s_waitcnt vmcnt(18)
	ds_write_b128 v68, v[224:227] offset:0
	ds_write_b128 v68, v[228:231] offset:1024
	ds_write_b128 v68, v[232:235] offset:2048
	ds_write_b128 v68, v[236:239] offset:3072
	ds_write_b128 v68, v[240:243] offset:4096
	ds_write_b128 v68, v[244:247] offset:5120
	ds_read_b128 v[72:75], v69 offset:0
	ds_read_b128 v[76:79], v69 offset:1024
	ds_read_b128 v[80:83], v69 offset:2048
	ds_read_b128 v[84:87], v69 offset:3072
	ds_read_b128 v[88:91], v69 offset:4096
	ds_read_b128 v[92:95], v69 offset:5120
	s_waitcnt lgkmcnt(12)
	global_load_dwordx4 v[200:203], v[44:45], off offset:512
	global_load_dwordx4 v[204:207], v[46:47], off offset:512
	global_load_dwordx4 v[208:211], v[60:61], off offset:512
	global_load_dwordx4 v[212:215], v[62:63], off offset:512
	global_load_dwordx4 v[216:219], v[64:65], off offset:512
	global_load_dwordx4 v[220:223], v[66:67], off offset:512
	v_mfma_f32_16x16x32_bf16 v[18:21], v[96:99], v[104:107], v[18:21]
	v_mfma_f32_16x16x32_bf16 v[48:51], v[96:99], v[108:111], v[48:51]
	v_mfma_f32_16x16x32_bf16 v[52:55], v[96:99], v[112:115], v[52:55]
	v_mfma_f32_16x16x32_bf16 v[28:31], v[96:99], v[116:119], v[28:31]
	v_mfma_f32_16x16x32_bf16 v[32:35], v[100:103], v[104:107], v[32:35]
	v_mfma_f32_16x16x32_bf16 v[36:39], v[100:103], v[108:111], v[36:39]
	v_mfma_f32_16x16x32_bf16 v[40:43], v[100:103], v[112:115], v[40:43]
	v_mfma_f32_16x16x32_bf16 v[2:5], v[100:103], v[116:119], v[2:5]
	s_waitcnt vmcnt(18)
	ds_write_b128 v68, v[120:123] offset:6144
	ds_write_b128 v68, v[124:127] offset:7168
	ds_write_b128 v68, v[128:131] offset:8192
	ds_write_b128 v68, v[132:135] offset:9216
	ds_write_b128 v68, v[136:139] offset:10240
	ds_write_b128 v68, v[140:143] offset:11264
	ds_read_b128 v[96:99], v69 offset:6144
	ds_read_b128 v[100:103], v69 offset:7168
	ds_read_b128 v[104:107], v69 offset:8192
	ds_read_b128 v[108:111], v69 offset:9216
	ds_read_b128 v[112:115], v69 offset:10240
	ds_read_b128 v[116:119], v69 offset:11264
	s_waitcnt lgkmcnt(12)
	global_load_dwordx4 v[224:227], v[44:45], off offset:576
	global_load_dwordx4 v[228:231], v[46:47], off offset:576
	global_load_dwordx4 v[232:235], v[60:61], off offset:576
	global_load_dwordx4 v[236:239], v[62:63], off offset:576
	global_load_dwordx4 v[240:243], v[64:65], off offset:576
	global_load_dwordx4 v[244:247], v[66:67], off offset:576
	v_mfma_f32_16x16x32_bf16 v[18:21], v[72:75], v[80:83], v[18:21]
	v_mfma_f32_16x16x32_bf16 v[48:51], v[72:75], v[84:87], v[48:51]
	v_mfma_f32_16x16x32_bf16 v[52:55], v[72:75], v[88:91], v[52:55]
	v_mfma_f32_16x16x32_bf16 v[28:31], v[72:75], v[92:95], v[28:31]
	v_mfma_f32_16x16x32_bf16 v[32:35], v[76:79], v[80:83], v[32:35]
	v_mfma_f32_16x16x32_bf16 v[36:39], v[76:79], v[84:87], v[36:39]
	v_mfma_f32_16x16x32_bf16 v[40:43], v[76:79], v[88:91], v[40:43]
	v_mfma_f32_16x16x32_bf16 v[2:5], v[76:79], v[92:95], v[2:5]
	s_waitcnt vmcnt(18)
	ds_write_b128 v68, v[144:147] offset:0
	ds_write_b128 v68, v[148:151] offset:1024
	ds_write_b128 v68, v[152:155] offset:2048
	ds_write_b128 v68, v[156:159] offset:3072
	ds_write_b128 v68, v[168:171] offset:4096
	ds_write_b128 v68, v[172:175] offset:5120
	ds_read_b128 v[72:75], v69 offset:0
	ds_read_b128 v[76:79], v69 offset:1024
	ds_read_b128 v[80:83], v69 offset:2048
	ds_read_b128 v[84:87], v69 offset:3072
	ds_read_b128 v[88:91], v69 offset:4096
	ds_read_b128 v[92:95], v69 offset:5120
	s_waitcnt lgkmcnt(12)
; #define LAS __attribute__((address_space(3)))
; #define MFMA16(a, b, c) __builtin_amdgcn_mfma_f32_16x16x32_bf16((a), (b), (c), 0, 0, 0)
; __device__ __forceinline__ void sk_tile(LAS unsigned char* lds, const bf16* A, int lda, const bf16* Wt, int K, int r0, int c0, int tid, int wave, int lane) {
;     ...
; #pragma unroll 2
;     for (int ks = 0; ks < (ksl >> 5); ++ks) {
;         bf16x8 af[2], bf[4];
; #pragma unroll
;         for (int m = 0; m < 2; ++m) af[m] = *(const bf16x8*)(ap + (size_t)(16 * m) * lda + 32 * ks);
; #pragma unroll
;         for (int j = 0; j < 4; ++j) bf[j] = *(const bf16x8*)(bp + (size_t)(16 * j) * K + 32 * ks);
; #pragma unroll
;         for (int m = 0; m < 2; ++m)
; #pragma unroll
;             for (int j = 0; j < 4; ++j) acc[m][j] = MFMA16(af[m], bf[j], acc[m][j]);
;     }
;     LAS float* part = (LAS float*)lds + wave * 2048;
; #pragma unroll
;     for (int m = 0; m < 2; ++m)
; #pragma unroll
;         for (int j = 0; j < 4; ++j)
; #pragma unroll
;             for (int e = 0; e < 4; ++e) part[(16 * m + 4 * kg + e) * 64 + 16 * j + r16] = acc[m][j][e];
;     __syncthreads();
	global_load_dwordx4 v[120:123], v[44:45], off offset:640
	global_load_dwordx4 v[124:127], v[46:47], off offset:640
	global_load_dwordx4 v[128:131], v[60:61], off offset:640
	global_load_dwordx4 v[132:135], v[62:63], off offset:640
	global_load_dwordx4 v[136:139], v[64:65], off offset:640
	global_load_dwordx4 v[140:143], v[66:67], off offset:640
	v_mfma_f32_16x16x32_bf16 v[18:21], v[96:99], v[104:107], v[18:21]
	v_mfma_f32_16x16x32_bf16 v[48:51], v[96:99], v[108:111], v[48:51]
	v_mfma_f32_16x16x32_bf16 v[52:55], v[96:99], v[112:115], v[52:55]
	v_mfma_f32_16x16x32_bf16 v[28:31], v[96:99], v[116:119], v[28:31]
	v_mfma_f32_16x16x32_bf16 v[32:35], v[100:103], v[104:107], v[32:35]
	v_mfma_f32_16x16x32_bf16 v[36:39], v[100:103], v[108:111], v[36:39]
	v_mfma_f32_16x16x32_bf16 v[40:43], v[100:103], v[112:115], v[40:43]
	v_mfma_f32_16x16x32_bf16 v[2:5], v[100:103], v[116:119], v[2:5]
	s_waitcnt vmcnt(18)
	ds_write_b128 v68, v[176:179] offset:6144
	ds_write_b128 v68, v[180:183] offset:7168
	ds_write_b128 v68, v[184:187] offset:8192
	ds_write_b128 v68, v[188:191] offset:9216
	ds_write_b128 v68, v[192:195] offset:10240
	ds_write_b128 v68, v[196:199] offset:11264
	ds_read_b128 v[96:99], v69 offset:6144
	ds_read_b128 v[100:103], v69 offset:7168
	ds_read_b128 v[104:107], v69 offset:8192
	ds_read_b128 v[108:111], v69 offset:9216
	ds_read_b128 v[112:115], v69 offset:10240
	ds_read_b128 v[116:119], v69 offset:11264
	s_waitcnt lgkmcnt(12)
	v_mfma_f32_16x16x32_bf16 v[18:21], v[72:75], v[80:83], v[18:21]
	v_mfma_f32_16x16x32_bf16 v[48:51], v[72:75], v[84:87], v[48:51]
	v_mfma_f32_16x16x32_bf16 v[52:55], v[72:75], v[88:91], v[52:55]
	v_mfma_f32_16x16x32_bf16 v[28:31], v[72:75], v[92:95], v[28:31]
	v_mfma_f32_16x16x32_bf16 v[32:35], v[76:79], v[80:83], v[32:35]
	v_mfma_f32_16x16x32_bf16 v[36:39], v[76:79], v[84:87], v[36:39]
	v_mfma_f32_16x16x32_bf16 v[40:43], v[76:79], v[88:91], v[40:43]
	v_mfma_f32_16x16x32_bf16 v[2:5], v[76:79], v[92:95], v[2:5]
	s_waitcnt vmcnt(12)
	ds_write_b128 v68, v[200:203] offset:0
	ds_write_b128 v68, v[204:207] offset:1024
	ds_write_b128 v68, v[208:211] offset:2048
	ds_write_b128 v68, v[212:215] offset:3072
	ds_write_b128 v68, v[216:219] offset:4096
	ds_write_b128 v68, v[220:223] offset:5120
	ds_read_b128 v[72:75], v69 offset:0
	ds_read_b128 v[76:79], v69 offset:1024
	ds_read_b128 v[80:83], v69 offset:2048
	ds_read_b128 v[84:87], v69 offset:3072
	ds_read_b128 v[88:91], v69 offset:4096
	ds_read_b128 v[92:95], v69 offset:5120
	s_waitcnt lgkmcnt(12)
	v_mfma_f32_16x16x32_bf16 v[18:21], v[96:99], v[104:107], v[18:21]
	v_mfma_f32_16x16x32_bf16 v[48:51], v[96:99], v[108:111], v[48:51]
	v_mfma_f32_16x16x32_bf16 v[52:55], v[96:99], v[112:115], v[52:55]
	v_mfma_f32_16x16x32_bf16 v[28:31], v[96:99], v[116:119], v[28:31]
	v_mfma_f32_16x16x32_bf16 v[32:35], v[100:103], v[104:107], v[32:35]
	v_mfma_f32_16x16x32_bf16 v[36:39], v[100:103], v[108:111], v[36:39]
	v_mfma_f32_16x16x32_bf16 v[40:43], v[100:103], v[112:115], v[40:43]
	v_mfma_f32_16x16x32_bf16 v[2:5], v[100:103], v[116:119], v[2:5]
	s_waitcnt vmcnt(6)
	ds_write_b128 v68, v[224:227] offset:6144
	ds_write_b128 v68, v[228:231] offset:7168
	ds_write_b128 v68, v[232:235] offset:8192
	ds_write_b128 v68, v[236:239] offset:9216
	ds_write_b128 v68, v[240:243] offset:10240
	ds_write_b128 v68, v[244:247] offset:11264
	ds_read_b128 v[96:99], v69 offset:6144
	ds_read_b128 v[100:103], v69 offset:7168
	ds_read_b128 v[104:107], v69 offset:8192
	ds_read_b128 v[108:111], v69 offset:9216
	ds_read_b128 v[112:115], v69 offset:10240
	ds_read_b128 v[116:119], v69 offset:11264
	s_waitcnt lgkmcnt(12)
	v_mfma_f32_16x16x32_bf16 v[18:21], v[72:75], v[80:83], v[18:21]
	v_mfma_f32_16x16x32_bf16 v[48:51], v[72:75], v[84:87], v[48:51]
	v_mfma_f32_16x16x32_bf16 v[52:55], v[72:75], v[88:91], v[52:55]
	v_mfma_f32_16x16x32_bf16 v[28:31], v[72:75], v[92:95], v[28:31]
	v_mfma_f32_16x16x32_bf16 v[32:35], v[76:79], v[80:83], v[32:35]
	v_mfma_f32_16x16x32_bf16 v[36:39], v[76:79], v[84:87], v[36:39]
	v_mfma_f32_16x16x32_bf16 v[40:43], v[76:79], v[88:91], v[40:43]
	v_mfma_f32_16x16x32_bf16 v[2:5], v[76:79], v[92:95], v[2:5]
	s_waitcnt vmcnt(0)
	ds_write_b128 v68, v[120:123] offset:0
	ds_write_b128 v68, v[124:127] offset:1024
	ds_write_b128 v68, v[128:131] offset:2048
	ds_write_b128 v68, v[132:135] offset:3072
	ds_write_b128 v68, v[136:139] offset:4096
	ds_write_b128 v68, v[140:143] offset:5120
	ds_read_b128 v[72:75], v69 offset:0
	ds_read_b128 v[76:79], v69 offset:1024
	ds_read_b128 v[80:83], v69 offset:2048
	ds_read_b128 v[84:87], v69 offset:3072
	ds_read_b128 v[88:91], v69 offset:4096
	ds_read_b128 v[92:95], v69 offset:5120
	s_waitcnt lgkmcnt(12)
	v_mfma_f32_16x16x32_bf16 v[18:21], v[96:99], v[104:107], v[18:21]
	v_mfma_f32_16x16x32_bf16 v[48:51], v[96:99], v[108:111], v[48:51]
	v_mfma_f32_16x16x32_bf16 v[52:55], v[96:99], v[112:115], v[52:55]
	v_mfma_f32_16x16x32_bf16 v[28:31], v[96:99], v[116:119], v[28:31]
	v_mfma_f32_16x16x32_bf16 v[32:35], v[100:103], v[104:107], v[32:35]
	v_mfma_f32_16x16x32_bf16 v[36:39], v[100:103], v[108:111], v[36:39]
	v_mfma_f32_16x16x32_bf16 v[40:43], v[100:103], v[112:115], v[40:43]
	v_mfma_f32_16x16x32_bf16 v[2:5], v[100:103], v[116:119], v[2:5]
	s_waitcnt lgkmcnt(0)
	v_mfma_f32_16x16x32_bf16 v[18:21], v[72:75], v[80:83], v[18:21]
	v_mfma_f32_16x16x32_bf16 v[48:51], v[72:75], v[84:87], v[48:51]
	v_mfma_f32_16x16x32_bf16 v[52:55], v[72:75], v[88:91], v[52:55]
	v_mfma_f32_16x16x32_bf16 v[28:31], v[72:75], v[92:95], v[28:31]
	v_mfma_f32_16x16x32_bf16 v[32:35], v[76:79], v[80:83], v[32:35]
	v_mfma_f32_16x16x32_bf16 v[36:39], v[76:79], v[84:87], v[36:39]
	v_mfma_f32_16x16x32_bf16 v[40:43], v[76:79], v[88:91], v[40:43]
	v_mfma_f32_16x16x32_bf16 v[2:5], v[76:79], v[92:95], v[2:5]
	s_nop 7
	s_nop 1
	s_barrier
; #define LAS __attribute__((address_space(3)))
; __device__ __forceinline__ unsigned long long rt() { return __builtin_amdgcn_s_memrealtime(); }
; __device__ __forceinline__ unsigned cvtpk(float lo, float hi) { f32x2_t v = {lo, hi}; bf16x2_t b = __builtin_convertvector(v, bf16x2_t); return __builtin_bit_cast(unsigned, b); }
; __device__ __forceinline__ void sk_tile(LAS unsigned char* lds, const bf16* A, int lda, const bf16* Wt, int K, int r0, int c0, int tid, int wave, int lane) {
;     ...
;     LAS float* part = (LAS float*)lds + wave * 2048;
; #pragma unroll
;     for (int m = 0; m < 2; ++m)
; #pragma unroll
;         for (int j = 0; j < 4; ++j)
; #pragma unroll
;             for (int e = 0; e < 4; ++e) part[(16 * m + 4 * kg + e) * 64 + 16 * j + r16] = acc[m][j][e];
;     __syncthreads();
;     {
;         const LAS f32x4* p4 = (const LAS f32x4*)lds + tid;
;         f32x4 s = p4[0];
; #pragma unroll
;         for (int w = 1; w < 8; ++w) s += p4[w * 512];
;         ((LAS f32x4*)(lds + 65536))[tid] = s;
;     }
;     __syncthreads();
; }
; __device__ __forceinline__ void sk_gemm_y(LAS unsigned char* lds, const bf16* A, int lda, const bf16* Wt, int K, bf16* Y, int tid, int wave, int lane) {
;     for (int item = blockIdx.x; item < 256; item += gridDim.x) {
;         const int rt = item >> 4, ct = item & 15;
;         sk_tile(lds, A, lda, Wt, K, MP + 32 * rt, 64 * ct, tid, wave, lane);
;         const f32x4 v = ((const LAS f32x4*)(lds + 65536))[tid];
;         *(uint2*)(Y + (size_t)(MP + 32 * rt + (tid >> 4)) * D + 64 * ct + 4 * (tid & 15)) = make_uint2(cvtpk(v[0], v[1]), cvtpk(v[2], v[3]));
;         __syncthreads();
	ds_write2_b32 v26, v18, v48 offset1:16
	ds_write2_b32 v26, v19, v49 offset0:64 offset1:80
	ds_write2_b32 v26, v20, v50 offset0:128 offset1:144
	ds_write2_b32 v26, v21, v51 offset0:192 offset1:208
	ds_write2_b32 v26, v52, v28 offset0:32 offset1:48
	ds_write2_b32 v26, v53, v29 offset0:96 offset1:112
	ds_write2_b32 v26, v54, v30 offset0:160 offset1:176
	ds_write2_b32 v26, v55, v31 offset0:224 offset1:240
	ds_write2_b32 v27, v32, v36 offset1:16
	ds_write2_b32 v27, v33, v37 offset0:64 offset1:80
	ds_write2_b32 v27, v34, v38 offset0:128 offset1:144
	ds_write2_b32 v27, v35, v39 offset0:192 offset1:208
	ds_write2_b32 v27, v40, v2 offset0:32 offset1:48
	ds_write2_b32 v27, v41, v3 offset0:96 offset1:112
	ds_write2_b32 v27, v42, v4 offset0:160 offset1:176
	ds_write2_b32 v27, v43, v5 offset0:224 offset1:240
	s_waitcnt lgkmcnt(0)
	s_barrier
	ds_read_b128 v[2:5], v23
	ds_read_b128 v[14:17], v23 offset:8192
	ds_read_b128 v[18:21], v23 offset:16384
	ds_read_b128 v[28:31], v23 offset:24576
	ds_read_b128 v[32:35], v23 offset:32768
	ds_read_b128 v[36:39], v23 offset:40960
	ds_read_b128 v[40:43], v23 offset:49152
	ds_read_b128 v[44:47], v23 offset:57344
	s_waitcnt lgkmcnt(6)
	v_pk_add_f32 v[4:5], v[4:5], v[16:17]
	v_pk_add_f32 v[2:3], v[2:3], v[14:15]
	s_waitcnt lgkmcnt(5)
	v_pk_add_f32 v[4:5], v[4:5], v[20:21]
	v_pk_add_f32 v[2:3], v[2:3], v[18:19]
	s_waitcnt lgkmcnt(4)
	v_pk_add_f32 v[4:5], v[4:5], v[30:31]
	v_pk_add_f32 v[2:3], v[2:3], v[28:29]
	s_waitcnt lgkmcnt(3)
	v_pk_add_f32 v[4:5], v[4:5], v[34:35]
	v_pk_add_f32 v[2:3], v[2:3], v[32:33]
	s_waitcnt lgkmcnt(2)
	v_pk_add_f32 v[4:5], v[4:5], v[38:39]
	v_pk_add_f32 v[2:3], v[2:3], v[36:37]
	s_waitcnt lgkmcnt(1)
	v_pk_add_f32 v[4:5], v[4:5], v[42:43]
	v_pk_add_f32 v[2:3], v[2:3], v[40:41]
	s_waitcnt lgkmcnt(0)
	v_pk_add_f32 v[4:5], v[4:5], v[46:47]
	v_pk_add_f32 v[2:3], v[2:3], v[44:45]
	ds_write_b128 v24, v[2:5]
	s_waitcnt lgkmcnt(0)
	s_barrier
	ds_read_b128 v[2:5], v24
	s_waitcnt lgkmcnt(0)
	v_cvt_pk_bf16_f32 v2, v2, v3
	v_cvt_pk_bf16_f32 v3, v4, v5
	global_store_dwordx2 v[56:57], v[2:3], off
	s_barrier
	s_cbranch_scc1 .LBB0_429

; #define LAS __attribute__((address_space(3)))
; __global__ void __launch_bounds__(NTHR, 2) mk_fwd(Args a) {
;     extern __shared__ __attribute__((aligned(16))) unsigned char lds_raw[];
;     LAS unsigned char* lds = (LAS unsigned char*)lds_raw;
	.amdhsa_kernel _Z6mk_fwd4Args
		.amdhsa_group_segment_fixed_size 0
		.amdhsa_private_segment_fixed_size 0
		.amdhsa_kernarg_size 432
		.amdhsa_user_sgpr_count 2
		.amdhsa_user_sgpr_dispatch_ptr 0
		.amdhsa_user_sgpr_queue_ptr 0
		.amdhsa_user_sgpr_kernarg_segment_ptr 1
		.amdhsa_user_sgpr_dispatch_id 0
		.amdhsa_user_sgpr_kernarg_preload_length 0
		.amdhsa_user_sgpr_kernarg_preload_offset 0
		.amdhsa_user_sgpr_private_segment_size 0
		.amdhsa_uses_dynamic_stack 0
		.amdhsa_enable_private_segment 0
		.amdhsa_system_sgpr_workgroup_id_x 1
		.amdhsa_system_sgpr_workgroup_id_y 0
		.amdhsa_system_sgpr_workgroup_id_z 0
		.amdhsa_system_sgpr_workgroup_info 0
		.amdhsa_system_vgpr_workitem_id 0
		.amdhsa_next_free_vgpr 256
		.amdhsa_next_free_sgpr 102
		.amdhsa_accum_offset 256
		.amdhsa_reserve_vcc 1
		.amdhsa_float_round_mode_32 0
		.amdhsa_float_round_mode_16_64 0
		.amdhsa_float_denorm_mode_32 3
		.amdhsa_float_denorm_mode_16_64 3
		.amdhsa_dx10_clamp 1
		.amdhsa_ieee_mode 1
		.amdhsa_fp16_overflow 0
		.amdhsa_tg_split 0
		.amdhsa_exception_fp_ieee_invalid_op 0
		.amdhsa_exception_fp_denorm_src 0
		.amdhsa_exception_fp_ieee_div_zero 0
		.amdhsa_exception_fp_ieee_overflow 0
		.amdhsa_exception_fp_ieee_underflow 0
		.amdhsa_exception_fp_ieee_inexact 0
		.amdhsa_exception_int_div_zero 0
	.end_amdhsa_kernel

; __global__ void __launch_bounds__(NTHR, 2) mk_fwd(Args a) {
;     extern __shared__ __attribute__((aligned(16))) unsigned char lds_raw[];
amdhsa.kernels:
  - .agpr_count:     0
    .args:
      - .offset:         0
        .size:           176
        .value_kind:     by_value
      - .offset:         176
        .size:           4
        .value_kind:     hidden_block_count_x
      - .offset:         180
        .size:           4
        .value_kind:     hidden_block_count_y
      - .offset:         184
        .size:           4
        .value_kind:     hidden_block_count_z
      - .offset:         188
        .size:           2
        .value_kind:     hidden_group_size_x
      - .offset:         190
        .size:           2
        .value_kind:     hidden_group_size_y
      - .offset:         192
        .size:           2
        .value_kind:     hidden_group_size_z
      - .offset:         194
        .size:           2
        .value_kind:     hidden_remainder_x
      - .offset:         196
        .size:           2
        .value_kind:     hidden_remainder_y
      - .offset:         198
        .size:           2
        .value_kind:     hidden_remainder_z
      - .offset:         216
        .size:           8
        .value_kind:     hidden_global_offset_x
      - .offset:         224
        .size:           8
        .value_kind:     hidden_global_offset_y
      - .offset:         232
        .size:           8
        .value_kind:     hidden_global_offset_z
      - .offset:         240
        .size:           2
        .value_kind:     hidden_grid_dims
      - .offset:         296
        .size:           4
        .value_kind:     hidden_dynamic_lds_size
    .group_segment_fixed_size: 0
    .kernarg_segment_align: 8
    .kernarg_segment_size: 432
    .language:       OpenCL C
    .language_version:
      - 2
      - 0
    .max_flat_workgroup_size: 512
    .name:           _Z6mk_fwd4Args
    .private_segment_fixed_size: 0
    .sgpr_count:     108
    .sgpr_spill_count: 82
    .symbol:         _Z6mk_fwd4Args.kd
    .uniform_work_group_size: 1
    .uses_dynamic_stack: false
    .vgpr_count:     256
    .vgpr_spill_count: 0
    .wavefront_size: 64
